# speedup vs baseline: 1.0360x; 1.0057x over previous
; DEV unsigned xb_ld(unsigned* p) { return __hip_atomic_load(p, __ATOMIC_RELAXED, __HIP_MEMORY_SCOPE_AGENT); }
; DEV unsigned xb_add(unsigned* p, unsigned v) { return __hip_atomic_fetch_add(p, v, __ATOMIC_RELAXED, __HIP_MEMORY_SCOPE_AGENT); }
; #define XB_SPIN(cond, bar) do { unsigned _sp = 0; while (cond) { __builtin_amdgcn_s_sleep(1); \
;     if ((++_sp & 255u) == 0u) { if (xb_ld(&(bar)[XB_TMO])) break; if (_sp > XB_SPIN_CAP) { atomicAdd(&(bar)[XB_TMO], 1u); break; } } } } while (0)
; DEV void xcd_barrier(unsigned* bar, volatile unsigned* st) {
;   asm volatile("s_waitcnt vmcnt(0)" ::: "memory");
;   __syncthreads();
;   if (threadIdx.x == 0) {
;     XcdBarrier b; b.bar = bar; b.x = st[0]; b.nloc = st[1]; b.nx = st[2];
;     __builtin_amdgcn_s_waitcnt(0);
;     const unsigned old = xb_add(&bar[XB_XSUB(b.x)], 1u);
;     const unsigned gen = old / b.nloc;
;     if (old + 1u == (gen + 1u) * b.nloc) {
;       __builtin_amdgcn_fence(__ATOMIC_RELEASE, "agent");
;       asm volatile("s_waitcnt vmcnt(0)" ::: "memory");
;       const unsigned og = xb_add(&bar[XB_TOP], 1u);
;       const unsigned tg = og / b.nx;
;       if (og + 1u == (tg + 1u) * b.nx) xb_add(&bar[XB_TOPGEN], 1u);
;       else XB_SPIN(xb_ld(&bar[XB_TOPGEN]) == tg, bar);
;       __builtin_amdgcn_fence(__ATOMIC_ACQUIRE, "agent");
;       xb_add(&bar[XB_XGEN(b.x)], 1u);
;     } else {
;       XB_SPIN(xb_ld(&bar[XB_XGEN(b.x)]) == gen, bar);
;       __builtin_amdgcn_fence(__ATOMIC_ACQUIRE, "agent");
;     }
;   }
;   __syncthreads();
; }
.LBB0_192:
	s_waitcnt vmcnt(0)
	s_barrier
	s_mov_b64 s[0:1], exec
	v_readlane_b32 s2, v254, 40
	v_readlane_b32 s3, v254, 41
	s_and_b64 s[2:3], s[0:1], s[2:3]
	s_mov_b64 exec, s[2:3]
	s_branch .LBB0_319
	v_mov_b32_e32 v133, v141
	flat_load_dword v1, v[132:133] sc0 sc1
	s_waitcnt vmcnt(0)
	v_mov_b32_e32 v135, v141
	flat_load_dword v4, v[134:135] sc0 sc1
	s_waitcnt vmcnt(0)
	v_mov_b32_e32 v137, v141
	flat_load_dword v0, v[136:137] sc0 sc1
	s_waitcnt vmcnt(0) expcnt(0) lgkmcnt(0)
	v_lshlrev_b32_e32 v1, 6, v1
	v_add_u32_e32 v128, 0x500, v1
	v_lshl_add_u64 v[2:3], v[128:129], 2, s[28:29]
	global_atomic_add v3, v[2:3], v172, off sc0
	v_cvt_f32_u32_e32 v2, v4
	v_sub_u32_e32 v5, 0, v4
	v_add_u32_e32 v128, 0x900, v1
	v_rcp_iflag_f32_e32 v2, v2
	s_nop 0
	v_mul_f32_e32 v2, 0x4f7ffffe, v2
	v_cvt_u32_f32_e32 v2, v2
	v_mul_lo_u32 v5, v5, v2
	v_mul_hi_u32 v5, v2, v5
	v_add_u32_e32 v2, v2, v5
	s_waitcnt vmcnt(0)
	v_mul_hi_u32 v2, v3, v2
	v_mul_lo_u32 v5, v2, v4
	v_sub_u32_e32 v5, v3, v5
	v_cmp_ge_u32_e32 vcc, v5, v4
	v_add_u32_e32 v6, 1, v2
	v_add_u32_e32 v3, 1, v3
	v_cndmask_b32_e32 v2, v2, v6, vcc
	v_sub_u32_e32 v6, v5, v4
	v_cndmask_b32_e32 v5, v5, v6, vcc
	v_cmp_ge_u32_e32 vcc, v5, v4
	v_add_u32_e32 v5, 1, v2
	s_nop 0
	v_cndmask_b32_e32 v2, v2, v5, vcc
	v_mad_u64_u32 v[4:5], s[2:3], v4, v2, v[4:5]
	v_cmp_ne_u32_e32 vcc, v3, v4
	s_and_saveexec_b64 s[2:3], vcc
	s_xor_b64 s[2:3], exec, s[2:3]
	s_cbranch_execz .LBB0_301
	v_lshl_add_u64 v[0:1], v[128:129], 2, s[28:29]
	global_load_dword v3, v[0:1], off sc1
	s_waitcnt vmcnt(0)
	v_cmp_eq_u32_e32 vcc, v3, v2
	s_and_saveexec_b64 s[4:5], vcc
	s_cbranch_execz .LBB0_300
	s_mov_b32 s20, 1
	s_mov_b64 s[6:7], 0
	s_branch .LBB0_291

; DEV unsigned xb_ld(unsigned* p) { return __hip_atomic_load(p, __ATOMIC_RELAXED, __HIP_MEMORY_SCOPE_AGENT); }
; DEV unsigned xb_add(unsigned* p, unsigned v) { return __hip_atomic_fetch_add(p, v, __ATOMIC_RELAXED, __HIP_MEMORY_SCOPE_AGENT); }
; #define XB_SPIN(cond, bar) do { unsigned _sp = 0; while (cond) { __builtin_amdgcn_s_sleep(1); \
;     if ((++_sp & 255u) == 0u) { if (xb_ld(&(bar)[XB_TMO])) break; if (_sp > XB_SPIN_CAP) { atomicAdd(&(bar)[XB_TMO], 1u); break; } } } } while (0)
; #define GSYNC() xcd_barrier(p.xbar, s_xb)
; DEV void xcd_barrier(unsigned* bar, volatile unsigned* st) {
;   asm volatile("s_waitcnt vmcnt(0)" ::: "memory");
;   __syncthreads();
;   if (threadIdx.x == 0) {
;     XcdBarrier b; b.bar = bar; b.x = st[0]; b.nloc = st[1]; b.nx = st[2];
;     __builtin_amdgcn_s_waitcnt(0);
;     const unsigned old = xb_add(&bar[XB_XSUB(b.x)], 1u);
;     const unsigned gen = old / b.nloc;
;     if (old + 1u == (gen + 1u) * b.nloc) {
;       __builtin_amdgcn_fence(__ATOMIC_RELEASE, "agent");
;       asm volatile("s_waitcnt vmcnt(0)" ::: "memory");
;       const unsigned og = xb_add(&bar[XB_TOP], 1u);
;       const unsigned tg = og / b.nx;
;       if (og + 1u == (tg + 1u) * b.nx) xb_add(&bar[XB_TOPGEN], 1u);
;       else XB_SPIN(xb_ld(&bar[XB_TOPGEN]) == tg, bar);
;       __builtin_amdgcn_fence(__ATOMIC_ACQUIRE, "agent");
;       xb_add(&bar[XB_XGEN(b.x)], 1u);
;     } else {
;       XB_SPIN(xb_ld(&bar[XB_XGEN(b.x)]) == gen, bar);
;       __builtin_amdgcn_fence(__ATOMIC_ACQUIRE, "agent");
;     }
;   }
;   __syncthreads();
; }
; __global__ void __launch_bounds__(NTHREADS, 2) fwd_megakernel(Params p) {
;     ...
;       phase_plegate(p, layer, grp, smem);
;       GSYNC();
.LBB0_917:
	s_waitcnt vmcnt(0)
	s_barrier
	s_mov_b64 s[0:1], exec
	v_readlane_b32 s2, v254, 40
	v_readlane_b32 s3, v254, 41
	s_and_b64 s[2:3], s[0:1], s[2:3]
	s_mov_b64 exec, s[2:3]
	v_readlane_b32 s4, v255, 32
	v_readlane_b32 s5, v255, 33
	s_or_b32 s4, s4, s5
	s_cmp_eq_u32 s4, 0
	s_cbranch_scc1 .LBB0_321
	s_cbranch_execz .LBB0_321
	v_mov_b32_e32 v133, v141
	flat_load_dword v1, v[132:133] sc0 sc1
	s_waitcnt vmcnt(0)
	v_mov_b32_e32 v135, v141
	flat_load_dword v4, v[134:135] sc0 sc1
	s_waitcnt vmcnt(0)
	v_mov_b32_e32 v137, v141
	flat_load_dword v0, v[136:137] sc0 sc1
	s_waitcnt vmcnt(0) expcnt(0) lgkmcnt(0)
	v_lshlrev_b32_e32 v1, 6, v1
	v_add_u32_e32 v128, 0x500, v1
	v_lshl_add_u64 v[2:3], v[128:129], 2, s[28:29]
	global_atomic_add v3, v[2:3], v172, off sc0
	v_cvt_f32_u32_e32 v2, v4
	v_sub_u32_e32 v5, 0, v4
	v_add_u32_e32 v128, 0x900, v1
	v_rcp_iflag_f32_e32 v2, v2
	s_nop 0
	v_mul_f32_e32 v2, 0x4f7ffffe, v2
	v_cvt_u32_f32_e32 v2, v2
	v_mul_lo_u32 v5, v5, v2
	v_mul_hi_u32 v5, v2, v5
	v_add_u32_e32 v2, v2, v5
	s_waitcnt vmcnt(0)
	v_mul_hi_u32 v2, v3, v2
	v_mul_lo_u32 v5, v2, v4
	v_sub_u32_e32 v5, v3, v5
	v_cmp_ge_u32_e32 vcc, v5, v4
	v_add_u32_e32 v6, 1, v2
	v_add_u32_e32 v3, 1, v3
	v_cndmask_b32_e32 v2, v2, v6, vcc
	v_sub_u32_e32 v6, v5, v4
	v_cndmask_b32_e32 v5, v5, v6, vcc
	v_cmp_ge_u32_e32 vcc, v5, v4
	v_add_u32_e32 v5, 1, v2
	s_nop 0
	v_cndmask_b32_e32 v2, v2, v5, vcc
	v_mad_u64_u32 v[4:5], s[2:3], v4, v2, v[4:5]
	v_cmp_ne_u32_e32 vcc, v3, v4
	s_and_saveexec_b64 s[2:3], vcc
	s_xor_b64 s[2:3], exec, s[2:3]
	s_cbranch_execz .LBB0_951
	v_lshl_add_u64 v[0:1], v[128:129], 2, s[28:29]
	global_load_dword v3, v[0:1], off sc1
	s_waitcnt vmcnt(0)
	v_cmp_eq_u32_e32 vcc, v3, v2
	s_and_saveexec_b64 s[4:5], vcc
	s_cbranch_execz .LBB0_950
	s_mov_b32 s22, 1
	s_mov_b64 s[6:7], 0
	s_branch .LBB0_941
